# hand-written weight-convert phase: scalar item decode, 16B saddr loads, next-item prefetch
# speedup vs baseline: 1.0030x; 1.0030x over previous
; __device__ __forceinline__ void phase_convert_weights(const Args& a, int l, LAS unsigned char* lds) {
;     const int tid = opaque_tid(), lane = tid & 63, wave = tid >> 6;
;     LAS float* scr = (LAS float*)(lds + wave * 16384);
;     const int gw = blockIdx.x * NWAVES + wave, NGW = gridDim.x * NWAVES;
;     constexpr int I_UP = 16 * 176, I_DN = 44 * 32, I_SQ = 16 * 32, I_L = 256;
;     constexpr int NITEMS = 3 * I_UP + 2 * I_DN + 3 * I_SQ + I_L;
;     unsigned char* ws = a.ws;
;     for (int it = gw; it < NITEMS; it += NGW) {
;         int r = it;
;         if (r < 2 * I_UP) {
;             const int which = r / I_UP; r -= which * I_UP;
;             const float* W = a.in[which ? I_UP2 : I_UP1] + (size_t)l * DM * NUP; bf16_t* WT = (bf16_t*)(ws + (which ? W_UP2 : W_UP1));
;             const int kb = r / 176, n0 = (r % 176) * 32, half = n0 / DFF, j = n0 % DFF;
;             transpose_item(W, DM, NUP, WT, kb, n0, 256 * (j / 128) + 128 * half + (j % 128), scr, lane); continue; }
;         r -= 2 * I_UP;
;         if (r < I_UP) { const int kb = r / 176, n0 = (r % 176) * 32;
;             transpose_item(a.in[I_WIN] + (size_t)l * DM * INC, DM, INC, (bf16_t*)(ws + W_IN), kb, n0, n0, scr, lane); continue; }
;         r -= I_UP;
;         if (r < 2 * I_DN) { const int which = r / I_DN; r -= which * I_DN;
;             const int kb = r / 32, n0 = (r % 32) * 32;
;             transpose_item(a.in[which ? I_DN2 : I_DN1] + (size_t)l * DFF * DM, DFF, DM, (bf16_t*)(ws + (which ? W_DN2 : W_DN1)), kb, n0, n0, scr, lane); continue; }
;         r -= 2 * I_DN;
;         if (r < 3 * I_SQ) { const int which = r / I_SQ; r -= which * I_SQ;
;             const int kb = r / 32, n0 = (r % 32) * 32;
;             const float* W = a.in[which == 0 ? I_WAO : (which == 1 ? I_WLO : I_WOUT)] + (size_t)l * DM * DM;
;             bf16_t* WT = (bf16_t*)(ws + (which == 0 ? W_AO : (which == 1 ? W_LO : W_OUT)));
;             transpose_item(W, DM, DM, WT, kb, n0, n0, scr, lane); continue; }
;         r -= 3 * I_SQ;
;         {
;             const int mat = r >> 3, sub = r & 7, kb = sub >> 2, n0 = (sub & 3) * 32;
;             const int type = mat & 1, d = (mat >> 1) & 1, hb = mat >> 2;
;             const float* W = a.in[type ? I_WX : I_WA] + (size_t)(((l * 2 + d) * 8 + hb)) * 128 * 128;
;             bf16_t* WT = (bf16_t*)(ws + W_LRU) + (size_t)((hb * 2 + d) * 2 + type) * 128 * 128;
.LBB0_488:
	s_mov_b64 s[16:17], exec
	v_readlane_b32 s48, v255, 7
	v_readlane_b32 s49, v255, 8
	v_readlane_b32 s19, v255, 15
	v_and_b32_e32 v0, 63, v196
	v_lshrrev_b32_e32 v7, 6, v196
	v_lshrrev_b32_e32 v1, 3, v0
	v_and_b32_e32 v2, 7, v0
	v_readfirstlane_b32 s24, v7
	v_lshlrev_b32_e32 v7, 14, v7
	v_mul_u32_u24_e32 v3, 33, v1
	v_lshl_add_u32 v3, v2, 2, v3
	v_lshl_add_u32 v3, v3, 2, v7
	v_mul_u32_u24_e32 v4, 0x108, v2
	v_add_u32_e32 v4, v4, v1
	v_lshl_add_u32 v4, v4, 2, v7
	v_lshlrev_b32_e32 v2, 4, v2
	s_lshl_b32 s0, s2, 3
	s_add_i32 s24, s24, s0
	s_cmpk_ge_i32 s24, 0x3300
	s_cbranch_scc1 .Lcv_done
	s_mov_b32 s42, 1.0
	s_cmpk_ge_i32 s24, 0x1600
	s_cbranch_scc1 .Lcv_notup1
	s_cmpk_ge_i32 s24, 0xb00
	s_cselect_b32 s26, 1, 0
	s_mulk_i32 s26, 0xb00
	s_sub_i32 s25, s24, s26
	s_cmp_lg_u32 s26, 0
	s_cselect_b32 s43, 0xa0, 0x28
	s_mov_b32 s52, 0x800000
	s_cselect_b32 s52, 0x2980000, s52
	s_mul_i32 s27, s25, 0xba2f
	s_lshr_b32 s27, s27, 23
	s_mul_i32 s0, s27, 176
	s_sub_i32 s28, s25, s0
	s_lshl_b32 s28, s28, 5
	s_cmpk_ge_i32 s28, 0xb00
	s_cselect_b32 s0, 0xb00, 0
	s_cselect_b32 s1, 128, 0
	s_sub_i32 s0, s28, s0
	s_lshr_b32 s29, s0, 7
	s_lshl_b32 s29, s29, 8
	s_and_b32 s0, s0, 127
	s_add_i32 s29, s29, s0
	s_add_i32 s29, s29, s1
	s_mul_i32 s51, s19, 0x1600000
	s_movk_i32 s36, 0x5800
	s_movk_i32 s37, 0x800
	s_branch .Lcv_common1
.Lcv_notup1:
	s_cmpk_ge_i32 s24, 0x2100
	s_cbranch_scc1 .Lcv_notwin1
	s_sub_i32 s25, s24, 0x1600
	s_mul_i32 s27, s25, 0xba2f
	s_lshr_b32 s27, s27, 23
	s_mul_i32 s0, s27, 176
	s_sub_i32 s28, s25, s0
	s_lshl_b32 s28, s28, 5
	s_mov_b32 s29, s28
	s_movk_i32 s43, 0x38
	s_mov_b32 s52, 0x1880000
	s_mul_i32 s51, s19, 0x1600000
	s_movk_i32 s36, 0x5800
	s_movk_i32 s37, 0x800
	s_branch .Lcv_common1
.Lcv_notwin1:
	s_cmpk_ge_i32 s24, 0x2c00
	s_cbranch_scc1 .Lcv_notdn1
	s_sub_i32 s25, s24, 0x2100
	s_cmpk_ge_i32 s25, 0x580
	s_cselect_b32 s0, 0x580, 0
	s_cselect_b32 s43, 0xa8, 0x30
	s_mov_b32 s52, 0x1300000
	s_cselect_b32 s52, 0x3480000, s52
	s_sub_i32 s25, s25, s0
	s_lshr_b32 s27, s25, 5
	s_and_b32 s28, s25, 31
	s_lshl_b32 s28, s28, 5
	s_mov_b32 s29, s28
	s_mul_i32 s51, s19, 0xb00000
	s_movk_i32 s36, 0x1000
	s_movk_i32 s37, 0x1600
	s_branch .Lcv_common1
.Lcv_notdn1:
	s_cmpk_ge_i32 s24, 0x3200
	s_cbranch_scc1 .Lcv_lru1
	s_sub_i32 s25, s24, 0x2c00
	s_lshr_b32 s26, s25, 9
	s_and_b32 s25, s25, 511
	s_lshr_b32 s27, s25, 5
	s_and_b32 s28, s25, 31
	s_lshl_b32 s28, s28, 5
	s_mov_b32 s29, s28
	s_lshl_b32 s43, s26, 3
	s_addk_i32 s43, 0x88
	s_lshl_b32 s52, s26, 21
	s_add_i32 s52, s52, 0x2380000
	s_lshl_b32 s51, s19, 22
	s_movk_i32 s36, 0x1000
	s_movk_i32 s37, 0x800
	s_branch .Lcv_common1
.Lcv_lru1:
	s_sub_i32 s25, s24, 0x3200
	s_lshr_b32 s26, s25, 3
	s_and_b32 s0, s25, 7
	s_lshr_b32 s27, s0, 2
	s_and_b32 s28, s0, 3
	s_lshl_b32 s28, s28, 5
	s_mov_b32 s29, s28
	s_and_b32 s0, s26, 1
	s_bfe_u32 s1, s26, 0x10001
	s_lshr_b32 s26, s26, 2
	s_cmp_lg_u32 s0, 0
	s_movk_i32 s43, 0x60
	s_cselect_b32 s43, 0x70, s43
	s_lshl_b32 s51, s19, 1
	s_add_i32 s51, s51, s1
	s_lshl_b32 s51, s51, 3
	s_add_i32 s51, s51, s26
	s_lshl_b32 s51, s51, 16
	s_lshl_b32 s52, s26, 1
	s_add_i32 s52, s52, s1
	s_lshl_b32 s52, s52, 1
	s_add_i32 s52, s52, s0
	s_lshl_b32 s52, s52, 15
	s_add_i32 s52, s52, 0x3a00000
	s_movk_i32 s36, 0x200
	s_movk_i32 s37, 0x100
	s_mov_b32 s42, 0xbfb8aa3b
.Lcv_common1:
	s_add_u32 s0, s48, s43
	s_addc_u32 s1, s49, 0
	s_load_dwordx2 s[30:31], s[0:1], 0x0
	s_lshl_b32 s26, s27, 6
	s_mul_i32 s25, s26, s36
	s_lshl_b32 s43, s28, 2
	s_add_i32 s25, s25, s43
	s_add_i32 s51, s51, s25
	s_mul_i32 s25, s29, s37
	s_lshl_b32 s26, s26, 1
	s_add_i32 s25, s25, s26
	s_add_i32 s52, s52, s25
	s_add_u32 s34, s22, s52
	s_addc_u32 s35, s23, 0
	s_waitcnt lgkmcnt(0)
	s_add_u32 s30, s30, s51
	s_addc_u32 s31, s31, 0
	v_mad_u32_u24 v5, v1, s36, v2
	s_lshl_b32 s0, s36, 3
	global_load_dwordx4 v[8:11], v5, s[30:31]
	v_add_u32_e32 v5, s0, v5
	global_load_dwordx4 v[12:15], v5, s[30:31]
	v_add_u32_e32 v5, s0, v5
	global_load_dwordx4 v[16:19], v5, s[30:31]
	v_add_u32_e32 v5, s0, v5
	global_load_dwordx4 v[20:23], v5, s[30:31]
	v_add_u32_e32 v5, s0, v5
	global_load_dwordx4 v[24:27], v5, s[30:31]
	v_add_u32_e32 v5, s0, v5
	global_load_dwordx4 v[28:31], v5, s[30:31]
	v_add_u32_e32 v5, s0, v5
	global_load_dwordx4 v[32:35], v5, s[30:31]
	v_add_u32_e32 v5, s0, v5
	global_load_dwordx4 v[36:39], v5, s[30:31]
.Lcv_loop:
	s_mov_b64 s[56:57], s[34:35]
	s_mov_b32 s53, s37
	s_mov_b32 s50, s42
	s_waitcnt vmcnt(0)
	ds_write_b32 v3, v8
	ds_write_b32 v3, v9 offset:4
	ds_write_b32 v3, v10 offset:8
	ds_write_b32 v3, v11 offset:12
	ds_write_b32 v3, v12 offset:1056
	ds_write_b32 v3, v13 offset:1060
	ds_write_b32 v3, v14 offset:1064
	ds_write_b32 v3, v15 offset:1068
	ds_write_b32 v3, v16 offset:2112
	ds_write_b32 v3, v17 offset:2116
	ds_write_b32 v3, v18 offset:2120
	ds_write_b32 v3, v19 offset:2124
	ds_write_b32 v3, v20 offset:3168
	ds_write_b32 v3, v21 offset:3172
	ds_write_b32 v3, v22 offset:3176
	ds_write_b32 v3, v23 offset:3180
	ds_write_b32 v3, v24 offset:4224
	ds_write_b32 v3, v25 offset:4228
	ds_write_b32 v3, v26 offset:4232
	ds_write_b32 v3, v27 offset:4236
	ds_write_b32 v3, v28 offset:5280
	ds_write_b32 v3, v29 offset:5284
	ds_write_b32 v3, v30 offset:5288
	ds_write_b32 v3, v31 offset:5292
	ds_write_b32 v3, v32 offset:6336
	ds_write_b32 v3, v33 offset:6340
	ds_write_b32 v3, v34 offset:6344
	ds_write_b32 v3, v35 offset:6348
	ds_write_b32 v3, v36 offset:7392
	ds_write_b32 v3, v37 offset:7396
	ds_write_b32 v3, v38 offset:7400
	ds_write_b32 v3, v39 offset:7404
	s_addk_i32 s24, 0x800
	s_cmpk_ge_i32 s24, 0x3300
	s_cbranch_scc1 .Lcv_nonext
	s_mov_b32 s42, 1.0
	s_cmpk_ge_i32 s24, 0x1600
	s_cbranch_scc1 .Lcv_notup2
	s_cmpk_ge_i32 s24, 0xb00
	s_cselect_b32 s26, 1, 0
	s_mulk_i32 s26, 0xb00
	s_sub_i32 s25, s24, s26
	s_cmp_lg_u32 s26, 0
	s_cselect_b32 s43, 0xa0, 0x28
	s_mov_b32 s52, 0x800000
	s_cselect_b32 s52, 0x2980000, s52
	s_mul_i32 s27, s25, 0xba2f
	s_lshr_b32 s27, s27, 23
	s_mul_i32 s0, s27, 176
	s_sub_i32 s28, s25, s0
	s_lshl_b32 s28, s28, 5
	s_cmpk_ge_i32 s28, 0xb00
	s_cselect_b32 s0, 0xb00, 0
	s_cselect_b32 s1, 128, 0
	s_sub_i32 s0, s28, s0
	s_lshr_b32 s29, s0, 7
	s_lshl_b32 s29, s29, 8
	s_and_b32 s0, s0, 127
	s_add_i32 s29, s29, s0
	s_add_i32 s29, s29, s1
	s_mul_i32 s51, s19, 0x1600000
	s_movk_i32 s36, 0x5800
	s_movk_i32 s37, 0x800
	s_branch .Lcv_common2

; __device__ __forceinline__ int opaque_tid() { int t = threadIdx.x; asm volatile("" : "+v"(t)); return t; }
; #define LAS __attribute__((address_space(3)))
; __device__ __forceinline__ unsigned pk2(float lo, float hi) { return pg8::cvt_pk_bf16(lo, hi); }
; #define LDS_WAIT() asm volatile("s_waitcnt lgkmcnt(0)" ::: "memory")
;     ...
;     LDS_WAIT();
;     const int c = lane & 7;
; #pragma unroll
;     for (int j = 0; j < 4; ++j) { const int n = (lane >> 3) + 8 * j; const LAS float* s = scr + (8 * c) * 33 + n;
;         u32x4 o; o.x = pk2(s[0 * 33] * sc, s[1 * 33] * sc); o.y = pk2(s[2 * 33] * sc, s[3 * 33] * sc); o.z = pk2(s[4 * 33] * sc, s[5 * 33] * sc); o.w = pk2(s[6 * 33] * sc, s[7 * 33] * sc);
;         *(u32x4*)(WT + (size_t)(outrow0 + n) * K + k0 + 8 * c) = o; }
;     LDS_WAIT();
; __device__ __forceinline__ void phase_norm(const float* xin, const float* g, const float* modl, int ishift, int iscale, bf16_t* H) {
;     const int tid = opaque_tid(), lane = tid & 63, wave = tid >> 6;
;     const int gw = blockIdx.x * NWAVES + wave, NGW = gridDim.x * NWAVES;
;     f32x4 v[4], vn[4];
;     if (gw < NT_TOK) {
; #pragma unroll
;         for (int j = 0; j < 4; ++j) v[j] = ((const f32x4*)(xin + (size_t)gw * DM) + lane)[64 * j];
;     }
;     for (int m = gw; m < NT_TOK; m += NGW) {
;         const int b = m >> 12, mn = m + NGW;
;         if (mn < NT_TOK) {
; #pragma unroll
;             for (int j = 0; j < 4; ++j) vn[j] = ((const f32x4*)(xin + (size_t)mn * DM) + lane)[64 * j];
;         }
.Lcv_nonext:
	v_mad_u32_u24 v6, v1, s53, v2
	s_lshl_b32 s0, s53, 3
	s_waitcnt lgkmcnt(0)
	ds_read_b32 v40, v4
	ds_read_b32 v41, v4 offset:132
	ds_read_b32 v42, v4 offset:264
	ds_read_b32 v43, v4 offset:396
	ds_read_b32 v44, v4 offset:528
	ds_read_b32 v45, v4 offset:660
	ds_read_b32 v46, v4 offset:792
	ds_read_b32 v47, v4 offset:924
	s_waitcnt lgkmcnt(0)
	v_mul_f32_e32 v40, s50, v40
	v_mul_f32_e32 v41, s50, v41
	v_mul_f32_e32 v42, s50, v42
	v_mul_f32_e32 v43, s50, v43
	v_mul_f32_e32 v44, s50, v44
	v_mul_f32_e32 v45, s50, v45
	v_mul_f32_e32 v46, s50, v46
	v_mul_f32_e32 v47, s50, v47
	v_cvt_pk_bf16_f32 v48, v40, v41
	v_cvt_pk_bf16_f32 v49, v42, v43
	v_cvt_pk_bf16_f32 v50, v44, v45
	v_cvt_pk_bf16_f32 v51, v46, v47
	global_store_dwordx4 v6, v[48:51], s[56:57]
	v_add_u32_e32 v6, s0, v6
	ds_read_b32 v40, v4 offset:32
	ds_read_b32 v41, v4 offset:164
	ds_read_b32 v42, v4 offset:296
	ds_read_b32 v43, v4 offset:428
	ds_read_b32 v44, v4 offset:560
	ds_read_b32 v45, v4 offset:692
	ds_read_b32 v46, v4 offset:824
	ds_read_b32 v47, v4 offset:956
	s_waitcnt lgkmcnt(0)
	v_mul_f32_e32 v40, s50, v40
	v_mul_f32_e32 v41, s50, v41
	v_mul_f32_e32 v42, s50, v42
	v_mul_f32_e32 v43, s50, v43
	v_mul_f32_e32 v44, s50, v44
	v_mul_f32_e32 v45, s50, v45
	v_mul_f32_e32 v46, s50, v46
	v_mul_f32_e32 v47, s50, v47
	v_cvt_pk_bf16_f32 v48, v40, v41
	v_cvt_pk_bf16_f32 v49, v42, v43
	v_cvt_pk_bf16_f32 v50, v44, v45
	v_cvt_pk_bf16_f32 v51, v46, v47
	global_store_dwordx4 v6, v[48:51], s[56:57]
	v_add_u32_e32 v6, s0, v6
	ds_read_b32 v40, v4 offset:64
	ds_read_b32 v41, v4 offset:196
	ds_read_b32 v42, v4 offset:328
	ds_read_b32 v43, v4 offset:460
	ds_read_b32 v44, v4 offset:592
	ds_read_b32 v45, v4 offset:724
	ds_read_b32 v46, v4 offset:856
	ds_read_b32 v47, v4 offset:988
	s_waitcnt lgkmcnt(0)
	v_mul_f32_e32 v40, s50, v40
	v_mul_f32_e32 v41, s50, v41
	v_mul_f32_e32 v42, s50, v42
	v_mul_f32_e32 v43, s50, v43
	v_mul_f32_e32 v44, s50, v44
	v_mul_f32_e32 v45, s50, v45
	v_mul_f32_e32 v46, s50, v46
	v_mul_f32_e32 v47, s50, v47
	v_cvt_pk_bf16_f32 v48, v40, v41
	v_cvt_pk_bf16_f32 v49, v42, v43
	v_cvt_pk_bf16_f32 v50, v44, v45
	v_cvt_pk_bf16_f32 v51, v46, v47
	global_store_dwordx4 v6, v[48:51], s[56:57]
	v_add_u32_e32 v6, s0, v6
	ds_read_b32 v40, v4 offset:96
	ds_read_b32 v41, v4 offset:228
	ds_read_b32 v42, v4 offset:360
	ds_read_b32 v43, v4 offset:492
	ds_read_b32 v44, v4 offset:624
	ds_read_b32 v45, v4 offset:756
	ds_read_b32 v46, v4 offset:888
	ds_read_b32 v47, v4 offset:1020
	s_waitcnt lgkmcnt(0)
	v_mul_f32_e32 v40, s50, v40
	v_mul_f32_e32 v41, s50, v41
	v_mul_f32_e32 v42, s50, v42
	v_mul_f32_e32 v43, s50, v43
	v_mul_f32_e32 v44, s50, v44
	v_mul_f32_e32 v45, s50, v45
	v_mul_f32_e32 v46, s50, v46
	v_mul_f32_e32 v47, s50, v47
	v_cvt_pk_bf16_f32 v48, v40, v41
	v_cvt_pk_bf16_f32 v49, v42, v43
	v_cvt_pk_bf16_f32 v50, v44, v45
	v_cvt_pk_bf16_f32 v51, v46, v47
	global_store_dwordx4 v6, v[48:51], s[56:57]
	s_cmpk_lt_i32 s24, 0x3300
	s_cbranch_scc1 .Lcv_loop
.Lcv_done:
	v_readlane_b32 s50, v255, 5
	v_readlane_b32 s51, v255, 6
.LBB0_507:
	s_or_b64 exec, exec, s[16:17]
	v_readlane_b32 s0, v255, 11
	v_readlane_b32 s30, v255, 3
	v_readlane_b32 s1, v255, 12
	v_readlane_b32 s48, v255, 1
	v_readlane_b32 s31, v255, 4
	s_andn2_b64 vcc, exec, s[0:1]
	v_readlane_b32 s49, v255, 2
	s_cbranch_vccnz .LBB0_514
	v_mov_b32_e32 v0, v196
	v_readlane_b32 s0, v254, 45
	v_ashrrev_i32_e32 v1, 6, v0
	s_nop 0
	v_add_u32_e32 v42, s0, v1
	v_cmp_gt_i32_e32 vcc, s64, v42
	s_and_saveexec_b64 s[16:17], vcc
	s_cbranch_execz .LBB0_513
	v_ashrrev_i32_e32 v43, 31, v42
	v_readlane_b32 s24, v255, 13
	v_and_b32_e32 v6, 63, v0
	v_lshlrev_b64 v[0:1], 12, v[42:43]
	v_readlane_b32 s25, v255, 14
	v_lshlrev_b32_e32 v4, 4, v6
	v_mov_b32_e32 v5, v144
	v_lshl_add_u64 v[0:1], s[24:25], 0, v[0:1]
	v_lshl_add_u64 v[0:1], v[0:1], 0, v[4:5]
	global_load_dwordx4 v[28:31], v[0:1], off
	global_load_dwordx4 v[12:15], v[0:1], off offset:1024
	global_load_dwordx4 v[8:11], v[0:1], off offset:2048
	s_nop 0
	global_load_dwordx4 v[0:3], v[0:1], off offset:3072
	v_readlane_b32 s0, v255, 7
	v_readlane_b32 s1, v255, 8
	s_load_dwordx2 s[0:1], s[0:1], 0x20
	v_lshl_add_u64 v[32:33], s[24:25], 0, v[4:5]
	s_mov_b64 s[24:25], 0
	s_waitcnt lgkmcnt(0)
	v_lshl_add_u64 v[34:35], s[0:1], 0, v[4:5]
	v_readlane_b32 s0, v255, 17
	v_readlane_b32 s1, v255, 18
	s_nop 1
	v_lshl_add_u64 v[36:37], s[0:1], 0, v[4:5]
	v_and_b32_e32 v4, 64, v198
	v_add_u32_e32 v4, 64, v4
	v_xor_b32_e32 v5, 1, v198
	v_cmp_lt_i32_e32 vcc, v5, v4
	v_readlane_b32 s0, v255, 19
	v_readlane_b32 s1, v255, 20
	v_cndmask_b32_e32 v5, v198, v5, vcc
	v_lshlrev_b32_e32 v44, 2, v5
	v_xor_b32_e32 v5, 2, v198
	v_cmp_lt_i32_e32 vcc, v5, v4
	s_nop 1
	v_cndmask_b32_e32 v5, v198, v5, vcc
	v_lshlrev_b32_e32 v45, 2, v5
	v_xor_b32_e32 v5, 4, v198
	v_cmp_lt_i32_e32 vcc, v5, v4
	s_nop 1
	v_cndmask_b32_e32 v5, v198, v5, vcc
	v_lshlrev_b32_e32 v46, 2, v5
	v_xor_b32_e32 v5, 8, v198
	v_cmp_lt_i32_e32 vcc, v5, v4
	s_nop 1
	v_cndmask_b32_e32 v5, v198, v5, vcc
	v_lshlrev_b32_e32 v47, 2, v5
	v_xor_b32_e32 v5, 16, v198
	v_cmp_lt_i32_e32 vcc, v5, v4
	s_nop 1
	v_cndmask_b32_e32 v5, v198, v5, vcc
	v_lshlrev_b32_e32 v48, 2, v5
	v_xor_b32_e32 v5, 32, v198
	v_cmp_lt_i32_e32 vcc, v5, v4
	s_nop 1
	v_cndmask_b32_e32 v4, v198, v5, vcc
	v_lshlrev_b32_e32 v49, 2, v4
	v_lshlrev_b64 v[4:5], 11, v[42:43]
	v_lshl_or_b32 v4, v6, 3, v4
	v_lshl_add_u64 v[38:39], s[0:1], 0, v[4:5]
	v_mov_b32_e32 v4, 0
	v_mov_b32_e32 v5, v4
	v_mov_b32_e32 v6, v4
	v_mov_b32_e32 v7, v4
	v_mov_b32_e32 v16, v4
	v_mov_b32_e32 v17, v4
	v_mov_b32_e32 v18, v4
	v_mov_b32_e32 v19, v4
	v_mov_b32_e32 v20, v4
	v_mov_b32_e32 v21, v4
	v_mov_b32_e32 v22, v4
	v_mov_b32_e32 v23, v4
	v_mov_b32_e32 v24, v4
	v_mov_b32_e32 v25, v4
	v_mov_b32_e32 v26, v4
	v_mov_b32_e32 v27, v4
	s_branch .LBB0_511
